# v31 + cross-attention: next-tile K/V loads as global_load (were flat_load waited at once via lgkmcnt), vmcnt wait moved to the LDS staging; K fragments read into six rotating registers several MFMAs a
# baseline (speedup 1.0000x reference)
; #define LAS __attribute__((address_space(3)))
; __device__ __forceinline__ float swap_max(float v) { auto rr = __builtin_amdgcn_permlane32_swap(__float_as_uint(v), __float_as_uint(v), false, false); return fmaxf(__uint_as_float(rr[0]), __uint_as_float(rr[1])); }
; #define ATT_LOADG() do { _Pragma("unroll") for (int i = 0; i < KPT; ++i) { if (KCH % 512 == 0 || kval[i]) kst[i] = *(const u32x4*)ksrc[i]; ksrc[i] += kinc[i]; } \
;                          _Pragma("unroll") for (int i = 0; i < VPT; ++i) { vst[i] = *(const u32x4*)vsrc[i]; vsrc[i] += vinc; } } while (0)
;     ...
;     for (int t = 0; t < ntiles; ++t) {
;         const int buf = t & 1; const bool more = (t + 1 < ntiles);
;         if (more) ATT_LOADG();
;         f32x16 s0, s1;
; #pragma unroll
;         for (int r = 0; r < 16; ++r) { s0[r] = 0.f; s1[r] = 0.f; }
;         { const LAS unsigned char* kb = Kb + buf * KBUF + krd;
; #pragma unroll
;           for (int d0 = 0; d0 < ND; ++d0) { const bf16x8 ka = *(const LAS bf16x8*)(kb + d0 * 32), kc = *(const LAS bf16x8*)(kb + 32 * RSK + d0 * 32);
;               s0 = __builtin_amdgcn_mfma_f32_32x32x16_bf16(ka, qf[d0], s0, 0, 0, 0); s1 = __builtin_amdgcn_mfma_f32_32x32x16_bf16(kc, qf[d0], s1, 0, 0, 0); } }
;         float mx = fmaxf(s0[0], s1[0]);
; #pragma unroll
;         for (int r = 1; r < 16; ++r) mx = fmaxf(mx, fmaxf(s0[r], s1[r]));
;         mx = swap_max(mx);
;         const float mn = fmaxf(mrun, mx), alpha = __builtin_amdgcn_exp2f(mrun - mn); mrun = mn;
;         float ps = 0.f;
; #pragma unroll
;         for (int r = 0; r < 16; ++r) { s0[r] = __builtin_amdgcn_exp2f(s0[r] - mn); s1[r] = __builtin_amdgcn_exp2f(s1[r] - mn); ps += s0[r] + s1[r]; }
.LBB0_49:
	global_load_dwordx4 v[98:101], v[150:151], off
	global_load_dwordx4 v[102:105], v[152:153], off
	global_load_dwordx4 v[106:109], v[154:155], off
	global_load_dwordx4 v[110:113], v[156:157], off
	v_lshl_add_u64 v[150:151], v[150:151], 0, s[18:19]
	v_lshl_add_u64 v[152:153], v[152:153], 0, s[18:19]
	v_lshl_add_u64 v[154:155], v[154:155], 0, s[18:19]
	v_lshl_add_u64 v[156:157], v[156:157], 0, s[18:19]
.LBB0_50:
	s_and_b32 s5, s4, 1
	s_mul_i32 s16, s5, 0x4400
	v_add_u32_e32 v172, s16, v166
	ds_read_b128 v[66:69], v172
	ds_read_b128 v[168:171], v172 offset:32
	ds_read_b128 v[82:85], v172 offset:8704
	s_lshl_b32 s16, s5, 14
	s_add_i32 s17, s16, 0
	s_andn2_b64 vcc, exec, s[14:15]
	ds_read_b128 v[228:231], v172 offset:8736
	ds_read_b128 v[232:235], v172 offset:64
	ds_read_b128 v[236:239], v172 offset:8768
	ds_read_b128 v[240:243], v172 offset:96
	ds_read_b128 v[244:247], v172 offset:8800
	ds_read_b128 v[248:251], v172 offset:128
	s_waitcnt lgkmcnt(8)
	v_mfma_f32_32x32x16_bf16 v[66:81], v[66:69], v[114:117], 0
	s_waitcnt lgkmcnt(7)
	v_mfma_f32_32x32x16_bf16 v[66:81], v[168:171], v[118:121], v[66:81]
	s_waitcnt lgkmcnt(6)
	v_mfma_f32_32x32x16_bf16 v[82:97], v[82:85], v[114:117], 0
	s_waitcnt lgkmcnt(5)
	v_mfma_f32_32x32x16_bf16 v[82:97], v[228:231], v[118:121], v[82:97]
	ds_read_b128 v[228:231], v172 offset:8832
	s_waitcnt lgkmcnt(5)
	v_mfma_f32_32x32x16_bf16 v[66:81], v[232:235], v[122:125], v[66:81]
	ds_read_b128 v[232:235], v172 offset:160
	s_waitcnt lgkmcnt(5)
	v_mfma_f32_32x32x16_bf16 v[82:97], v[236:239], v[122:125], v[82:97]
	ds_read_b128 v[236:239], v172 offset:8864
	s_waitcnt lgkmcnt(5)
	v_mfma_f32_32x32x16_bf16 v[66:81], v[240:243], v[126:129], v[66:81]
	ds_read_b128 v[240:243], v172 offset:192
	s_waitcnt lgkmcnt(5)
	v_mfma_f32_32x32x16_bf16 v[82:97], v[244:247], v[126:129], v[82:97]
	ds_read_b128 v[244:247], v172 offset:8896
	s_waitcnt lgkmcnt(5)
	v_mfma_f32_32x32x16_bf16 v[66:81], v[248:251], v[130:133], v[66:81]
	ds_read_b128 v[248:251], v172 offset:8928
	s_waitcnt lgkmcnt(5)
	v_mfma_f32_32x32x16_bf16 v[82:97], v[228:231], v[130:133], v[82:97]
	ds_read_b128 v[228:231], v172 offset:224
	s_waitcnt lgkmcnt(5)
	v_mfma_f32_32x32x16_bf16 v[66:81], v[232:235], v[134:137], v[66:81]
	s_waitcnt lgkmcnt(4)
	v_mfma_f32_32x32x16_bf16 v[82:97], v[236:239], v[134:137], v[82:97]
	s_waitcnt lgkmcnt(3)
	v_mfma_f32_32x32x16_bf16 v[66:81], v[240:243], v[138:141], v[66:81]
	s_waitcnt lgkmcnt(2)
	v_mfma_f32_32x32x16_bf16 v[82:97], v[244:247], v[138:141], v[82:97]
	s_waitcnt lgkmcnt(1)
	v_mfma_f32_32x32x16_bf16 v[82:97], v[248:251], v[142:145], v[82:97]
	s_waitcnt lgkmcnt(0)
	v_mfma_f32_32x32x16_bf16 v[66:81], v[228:231], v[142:145], v[66:81]
	s_nop 8
	v_max_f32_e32 v172, v83, v83
	v_max_f32_e32 v169, v84, v84
	s_nop 0
	v_max_f32_e32 v168, v67, v67
	v_max_f32_e32 v170, v68, v68
	v_max_f32_e32 v168, v168, v172
	v_max_f32_e32 v169, v170, v169
	v_max_f32_e32 v170, v85, v85
	v_max_f32_e32 v171, v69, v69
	v_max3_f32 v168, v66, v82, v168
	v_max_f32_e32 v170, v171, v170
	v_max3_f32 v168, v168, v169, v170
	v_max_f32_e32 v169, v86, v86
	v_max_f32_e32 v170, v70, v70
	v_max_f32_e32 v169, v170, v169
	v_max_f32_e32 v170, v87, v87
	v_max_f32_e32 v171, v71, v71
	v_max_f32_e32 v170, v171, v170
	v_max3_f32 v168, v168, v169, v170
	v_max_f32_e32 v169, v88, v88
	v_max_f32_e32 v170, v72, v72
	v_max_f32_e32 v169, v170, v169
	v_max_f32_e32 v170, v89, v89
	v_max_f32_e32 v171, v73, v73
	v_max_f32_e32 v170, v171, v170
	v_max3_f32 v168, v168, v169, v170
	v_max_f32_e32 v169, v90, v90
	v_max_f32_e32 v170, v74, v74
	v_max_f32_e32 v169, v170, v169
	v_max_f32_e32 v170, v91, v91
	v_max_f32_e32 v171, v75, v75
	v_max_f32_e32 v170, v171, v170
	v_max3_f32 v168, v168, v169, v170
	v_max_f32_e32 v169, v92, v92
	v_max_f32_e32 v170, v76, v76
	v_max_f32_e32 v169, v170, v169
	v_max_f32_e32 v170, v93, v93
	v_max_f32_e32 v171, v77, v77
	v_max_f32_e32 v170, v171, v170
	v_max3_f32 v168, v168, v169, v170
	v_max_f32_e32 v169, v94, v94
	v_max_f32_e32 v170, v78, v78
	v_max_f32_e32 v169, v170, v169
	v_max_f32_e32 v170, v95, v95
	v_max_f32_e32 v171, v79, v79
	v_max_f32_e32 v170, v171, v170
	v_max3_f32 v168, v168, v169, v170
	v_max_f32_e32 v169, v96, v96
	v_max_f32_e32 v170, v80, v80
	v_max_f32_e32 v169, v170, v169
	v_max_f32_e32 v170, v97, v97
	v_max_f32_e32 v171, v81, v81
	v_max_f32_e32 v170, v171, v170
	v_max3_f32 v168, v168, v169, v170
	v_mov_b32_e32 v169, v168
	s_nop 1
	v_permlane32_swap_b32_e32 v168, v169
	v_max3_f32 v168, v0, v168, v169
	v_add_u32_e32 v169, s17, v161
	v_sub_f32_e32 v0, v0, v168
	v_sub_f32_e32 v66, v66, v168
	v_sub_f32_e32 v67, v67, v168
	v_sub_f32_e32 v68, v68, v168
	v_sub_f32_e32 v69, v69, v168
	v_sub_f32_e32 v70, v70, v168
	v_sub_f32_e32 v71, v71, v168
	v_sub_f32_e32 v72, v72, v168
	v_sub_f32_e32 v73, v73, v168
	v_add3_u32 v169, v169, v162, v160
	v_exp_f32_e32 v66, v66
	v_exp_f32_e32 v67, v67
	v_exp_f32_e32 v68, v68
	v_exp_f32_e32 v69, v69
	v_exp_f32_e32 v70, v70
	v_exp_f32_e32 v71, v71
	v_exp_f32_e32 v72, v72
	v_exp_f32_e32 v73, v73
	v_exp_f32_e32 v0, v0
	ds_read_b64_tr_b16 v[170:171], v169 offset:34816
	ds_read_b64_tr_b16 v[172:173], v169 offset:36864
	v_cvt_pk_bf16_f32 v174, v66, v67
	v_cvt_pk_bf16_f32 v175, v68, v69
	v_pk_mul_f32 v[64:65], v[64:65], v[0:1] op_sel_hi:[1,0]
	v_pk_mul_f32 v[62:63], v[62:63], v[0:1] op_sel_hi:[1,0]
	v_pk_mul_f32 v[60:61], v[60:61], v[0:1] op_sel_hi:[1,0]
	v_pk_mul_f32 v[58:59], v[58:59], v[0:1] op_sel_hi:[1,0]
	v_pk_mul_f32 v[56:57], v[56:57], v[0:1] op_sel_hi:[1,0]
	v_pk_mul_f32 v[54:55], v[54:55], v[0:1] op_sel_hi:[1,0]
	v_pk_mul_f32 v[52:53], v[52:53], v[0:1] op_sel_hi:[1,0]
	v_pk_mul_f32 v[50:51], v[50:51], v[0:1] op_sel_hi:[1,0]
	v_cvt_pk_bf16_f32 v176, v70, v71
	v_cvt_pk_bf16_f32 v177, v72, v73
	v_sub_f32_e32 v74, v74, v168
	v_sub_f32_e32 v75, v75, v168
	s_waitcnt lgkmcnt(0)
; #define LAS __attribute__((address_space(3)))
; __device__ __forceinline__ unsigned pk2(float lo, float hi) { f32x2_t v = {lo, hi}; bf16x2_t b = __builtin_convertvector(v, bf16x2_t); return __builtin_bit_cast(unsigned, b); }
; #define ATT_STORE(buf) do { _Pragma("unroll") for (int i = 0; i < KPT; ++i) { if (KCH % 512 == 0 || kval[i]) *(LAS u32x4*)(Kb + (buf) * KBUF + kdst[i]) = kst[i]; } \
;                             _Pragma("unroll") for (int i = 0; i < VPT; ++i) { *(LAS u32x4*)(Vb + (buf) * VBUF + vdst[i]) = vst[i]; } } while (0)
;     ...
;         for (int r = 0; r < 16; ++r) { s0[r] = __builtin_amdgcn_exp2f(s0[r] - mn); s1[r] = __builtin_amdgcn_exp2f(s1[r] - mn); ps += s0[r] + s1[r]; }
;         l = l * alpha + ps;
; #pragma unroll
;         for (int dvb = 0; dvb < NDV; ++dvb)
; #pragma unroll
;             for (int r = 0; r < 16; ++r) o[dvb][r] *= alpha;
;         bf16x8 pf[4];
;         { u32x4 w;
;           w.x = pk2(s0[0], s0[1]); w.y = pk2(s0[2], s0[3]); w.z = pk2(s0[4], s0[5]); w.w = pk2(s0[6], s0[7]); pf[0] = __builtin_bit_cast(bf16x8, w);
;           w.x = pk2(s0[8], s0[9]); w.y = pk2(s0[10], s0[11]); w.z = pk2(s0[12], s0[13]); w.w = pk2(s0[14], s0[15]); pf[1] = __builtin_bit_cast(bf16x8, w);
;           w.x = pk2(s1[0], s1[1]); w.y = pk2(s1[2], s1[3]); w.z = pk2(s1[4], s1[5]); w.w = pk2(s1[6], s1[7]); pf[2] = __builtin_bit_cast(bf16x8, w);
;           w.x = pk2(s1[8], s1[9]); w.y = pk2(s1[10], s1[11]); w.z = pk2(s1[12], s1[13]); w.w = pk2(s1[14], s1[15]); pf[3] = __builtin_bit_cast(bf16x8, w); }
;         { const LAS unsigned char* vb = Vb + buf * VBUF;
; #pragma unroll
;           for (int dvb = 0; dvb < NDV; ++dvb)
; #pragma unroll
;               for (int ks = 0; ks < 4; ++ks) {
;                   const s16x4 lo = __builtin_bit_cast(s16x4, __builtin_amdgcn_ds_read_tr16_b64_v4i16((LAS s16x4*)(vb + vrd[dvb] + (ks * 16) * RSV)));
;                   const s16x4 h4 = __builtin_bit_cast(s16x4, __builtin_amdgcn_ds_read_tr16_b64_v4i16((LAS s16x4*)(vb + vrd[dvb] + (ks * 16 + 8) * RSV)));
;                   const bf16x8 vf = (bf16x8){lo[0], lo[1], lo[2], lo[3], h4[0], h4[1], h4[2], h4[3]};
;                   o[dvb] = __builtin_amdgcn_mfma_f32_32x32x16_bf16(vf, pf[ks], o[dvb], 0, 0, 0); } }
;         if (more) ATT_STORE(buf ^ 1);
;         __syncthreads();
	v_mfma_f32_32x32x16_bf16 v[50:65], v[170:173], v[174:177], v[50:65]
	v_sub_f32_e32 v76, v76, v168
	v_sub_f32_e32 v77, v77, v168
	v_sub_f32_e32 v78, v78, v168
	v_sub_f32_e32 v79, v79, v168
	v_sub_f32_e32 v80, v80, v168
	v_sub_f32_e32 v81, v81, v168
	v_exp_f32_e32 v74, v74
	v_exp_f32_e32 v75, v75
	v_exp_f32_e32 v76, v76
	v_exp_f32_e32 v77, v77
	v_exp_f32_e32 v78, v78
	v_exp_f32_e32 v79, v79
	v_exp_f32_e32 v80, v80
	v_exp_f32_e32 v81, v81
	ds_read_b64_tr_b16 v[178:179], v169 offset:38912
	ds_read_b64_tr_b16 v[180:181], v169 offset:40960
	v_cvt_pk_bf16_f32 v170, v74, v75
	v_cvt_pk_bf16_f32 v171, v76, v77
	v_cvt_pk_bf16_f32 v172, v78, v79
	v_cvt_pk_bf16_f32 v173, v80, v81
	v_sub_f32_e32 v82, v82, v168
	v_sub_f32_e32 v83, v83, v168
	s_waitcnt lgkmcnt(0)
	v_mfma_f32_32x32x16_bf16 v[50:65], v[178:181], v[170:173], v[50:65]
	v_sub_f32_e32 v84, v84, v168
	v_sub_f32_e32 v85, v85, v168
	v_sub_f32_e32 v86, v86, v168
	v_sub_f32_e32 v87, v87, v168
	v_sub_f32_e32 v88, v88, v168
	v_sub_f32_e32 v89, v89, v168
	v_exp_f32_e32 v82, v82
	v_exp_f32_e32 v83, v83
	v_exp_f32_e32 v84, v84
	v_exp_f32_e32 v85, v85
	v_exp_f32_e32 v86, v86
	v_exp_f32_e32 v87, v87
	v_exp_f32_e32 v88, v88
	v_exp_f32_e32 v89, v89
	ds_read_b64_tr_b16 v[182:183], v169 offset:43008
	ds_read_b64_tr_b16 v[184:185], v169 offset:45056
	v_cvt_pk_bf16_f32 v178, v82, v83
	v_cvt_pk_bf16_f32 v179, v84, v85
	v_cvt_pk_bf16_f32 v180, v86, v87
	v_cvt_pk_bf16_f32 v181, v88, v89
	ds_read_b64_tr_b16 v[186:187], v169 offset:47104
	ds_read_b64_tr_b16 v[188:189], v169 offset:49152
	v_add3_u32 v169, s17, v163, v160
	s_waitcnt lgkmcnt(2)
	v_mfma_f32_32x32x16_bf16 v[50:65], v[182:185], v[178:181], v[50:65]
	ds_read_b64_tr_b16 v[190:191], v169 offset:34816
	ds_read_b64_tr_b16 v[192:193], v169 offset:36864
	v_sub_f32_e32 v90, v90, v168
	v_sub_f32_e32 v91, v91, v168
	v_sub_f32_e32 v92, v92, v168
	v_sub_f32_e32 v93, v93, v168
	v_sub_f32_e32 v94, v94, v168
	v_sub_f32_e32 v95, v95, v168
	v_sub_f32_e32 v96, v96, v168
	v_sub_f32_e32 v97, v97, v168
	v_exp_f32_e32 v90, v90
	v_exp_f32_e32 v91, v91
	v_exp_f32_e32 v92, v92
	v_exp_f32_e32 v93, v93
	v_exp_f32_e32 v94, v94
	v_exp_f32_e32 v95, v95
	v_exp_f32_e32 v96, v96
	v_exp_f32_e32 v97, v97
	v_pk_mul_f32 v[48:49], v[48:49], v[0:1] op_sel_hi:[1,0]
	v_pk_mul_f32 v[46:47], v[46:47], v[0:1] op_sel_hi:[1,0]
	v_pk_mul_f32 v[44:45], v[44:45], v[0:1] op_sel_hi:[1,0]
	v_pk_mul_f32 v[42:43], v[42:43], v[0:1] op_sel_hi:[1,0]
	v_pk_mul_f32 v[40:41], v[40:41], v[0:1] op_sel_hi:[1,0]
	v_pk_mul_f32 v[38:39], v[38:39], v[0:1] op_sel_hi:[1,0]
	v_pk_mul_f32 v[36:37], v[36:37], v[0:1] op_sel_hi:[1,0]
	v_pk_mul_f32 v[34:35], v[34:35], v[0:1] op_sel_hi:[1,0]
	v_cvt_pk_bf16_f32 v182, v90, v91
	v_cvt_pk_bf16_f32 v183, v92, v93
	s_waitcnt lgkmcnt(0)
	v_mfma_f32_32x32x16_bf16 v[34:49], v[190:193], v[174:177], v[34:49]
	v_cvt_pk_bf16_f32 v184, v94, v95
	v_cvt_pk_bf16_f32 v185, v96, v97
	v_mul_f32_e64 v32, v32, v0
	v_mul_f32_e64 v33, v33, v0
	v_mul_f32_e64 v30, v30, v0
	v_mul_f32_e64 v31, v31, v0
	v_pk_mul_f32 v[28:29], v[28:29], v[0:1] op_sel_hi:[1,0]
	v_pk_mul_f32 v[26:27], v[26:27], v[0:1] op_sel_hi:[1,0]
	v_pk_mul_f32 v[24:25], v[24:25], v[0:1] op_sel_hi:[1,0]
	v_mfma_f32_32x32x16_bf16 v[50:65], v[186:189], v[182:185], v[50:65]
	ds_read_b64_tr_b16 v[186:187], v169 offset:38912
	ds_read_b64_tr_b16 v[188:189], v169 offset:40960
	v_mul_f32_e64 v22, v22, v0
	v_mul_f32_e64 v23, v23, v0
	v_mul_f32_e64 v20, v20, v0
	v_mul_f32_e64 v21, v21, v0
	v_pk_mul_f32 v[18:19], v[18:19], v[0:1] op_sel_hi:[1,0]
	v_pk_mul_f32 v[16:17], v[16:17], v[0:1] op_sel_hi:[1,0]
	v_pk_mul_f32 v[14:15], v[14:15], v[0:1] op_sel_hi:[1,0]
	v_pk_mul_f32 v[12:13], v[12:13], v[0:1] op_sel_hi:[1,0]
	s_waitcnt lgkmcnt(0)
	v_mfma_f32_32x32x16_bf16 v[34:49], v[186:189], v[170:173], v[34:49]
	ds_read_b64_tr_b16 v[186:187], v169 offset:43008
	ds_read_b64_tr_b16 v[188:189], v169 offset:45056
	v_mul_f32_e64 v10, v10, v0
	v_mul_f32_e64 v11, v11, v0
	v_mul_f32_e64 v8, v8, v0
	v_mul_f32_e64 v9, v9, v0
	v_pk_mul_f32 v[6:7], v[6:7], v[0:1] op_sel_hi:[1,0]
	v_pk_mul_f32 v[4:5], v[4:5], v[0:1] op_sel_hi:[1,0]
	v_pk_mul_f32 v[2:3], v[2:3], v[0:1] op_sel_hi:[1,0]
	s_waitcnt lgkmcnt(0)
	v_mfma_f32_32x32x16_bf16 v[34:49], v[186:189], v[178:181], v[34:49]
	ds_read_b64_tr_b16 v[186:187], v169 offset:47104
	ds_read_b64_tr_b16 v[188:189], v169 offset:49152
	v_add3_u32 v169, s17, v164, v160
	ds_read_b64_tr_b16 v[190:191], v169 offset:34816
	ds_read_b64_tr_b16 v[192:193], v169 offset:36864
	s_waitcnt lgkmcnt(0)
	v_mfma_f32_32x32x16_bf16 v[18:33], v[190:193], v[174:177], v[18:33]
	v_mfma_f32_32x32x16_bf16 v[34:49], v[186:189], v[182:185], v[34:49]
	ds_read_b64_tr_b16 v[186:187], v169 offset:38912
	ds_read_b64_tr_b16 v[188:189], v169 offset:40960
	s_waitcnt lgkmcnt(0)
	v_mfma_f32_32x32x16_bf16 v[18:33], v[186:189], v[170:173], v[18:33]
	ds_read_b64_tr_b16 v[186:187], v169 offset:43008
	ds_read_b64_tr_b16 v[188:189], v169 offset:45056
	s_waitcnt lgkmcnt(0)
	v_mfma_f32_32x32x16_bf16 v[18:33], v[186:189], v[178:181], v[18:33]
	ds_read_b64_tr_b16 v[186:187], v169 offset:47104
	ds_read_b64_tr_b16 v[188:189], v169 offset:49152
	v_add3_u32 v169, s17, v165, v160
	ds_read_b64_tr_b16 v[190:191], v169 offset:34816
	ds_read_b64_tr_b16 v[192:193], v169 offset:36864
	s_waitcnt lgkmcnt(0)
	v_mfma_f32_32x32x16_bf16 v[2:17], v[190:193], v[174:177], v[2:17]
	ds_read_b64_tr_b16 v[174:175], v169 offset:38912
	ds_read_b64_tr_b16 v[176:177], v169 offset:40960
	s_waitcnt lgkmcnt(0)
	v_mfma_f32_32x32x16_bf16 v[2:17], v[174:177], v[170:173], v[2:17]
	ds_read_b64_tr_b16 v[170:171], v169 offset:43008
	ds_read_b64_tr_b16 v[172:173], v169 offset:45056
	s_waitcnt lgkmcnt(0)
	v_mfma_f32_32x32x16_bf16 v[2:17], v[170:173], v[178:181], v[2:17]
	ds_read_b64_tr_b16 v[170:171], v169 offset:47104
	ds_read_b64_tr_b16 v[172:173], v169 offset:49152
	v_mfma_f32_32x32x16_bf16 v[18:33], v[186:189], v[182:185], v[18:33]
	s_waitcnt lgkmcnt(0)
	v_mfma_f32_32x32x16_bf16 v[2:17], v[170:173], v[182:185], v[2:17]
	s_cbranch_vccnz .LBB0_52
	s_xor_b32 s5, s5, 1
	s_mulk_i32 s5, 0x4400
	s_xor_b32 s14, s16, 0x4000
	s_add_i32 s5, s5, 0
	s_add_i32 s14, s14, 0
	v_add_u32_e32 v172, s5, v147
	v_add_u32_e32 v169, s14, v159
	v_add_u32_e32 v170, s14, v158
	v_add_u32_e32 v171, s5, v149
	s_waitcnt vmcnt(0)
	ds_write_b128 v172, v[98:101]
	ds_write_b128 v171, v[102:105]
	ds_write_b128 v170, v[106:109] offset:34816
	ds_write_b128 v169, v[110:113] offset:34816
